# strategy: stagger of SIMD partner waves in the attention compute (one wave of each pair starts 640 cycles later), on top of the no-setprio version
# baseline (speedup 1.0000x reference)
.LBB0_453:
	s_or_b64 exec, exec, s[0:1]
	s_lshl_b32 s0, s6, 2
	v_readlane_b32 s1, v252, 25
	s_add_i32 s34, s0, s1
	s_lshl_b32 s0, s34, 2
	s_waitcnt vmcnt(0)
	ds_write_b128 v168, v[12:15]
	ds_write_b128 v169, v[16:19]
	ds_write_b128 v170, v[20:23]
	ds_write_b128 v171, v[24:27]
	ds_write_b16 v172, v28 offset:36864
	ds_write_b16_d16_hi v172, v28 offset:37392
	ds_write_b16 v172, v29 offset:37920
	ds_write_b16_d16_hi v172, v29 offset:38448
	ds_write_b16 v172, v30 offset:38976
	ds_write_b16_d16_hi v172, v30 offset:39504
	ds_write_b16 v172, v31 offset:40032
	ds_write_b16_d16_hi v172, v31 offset:40560
	ds_write_b16 v173, v32 offset:36864
	ds_write_b16_d16_hi v173, v32 offset:37392
	ds_write_b16 v173, v33 offset:37920
	ds_write_b16_d16_hi v173, v33 offset:38448
	ds_write_b16 v173, v34 offset:38976
	ds_write_b16_d16_hi v173, v34 offset:39504
	ds_write_b16 v173, v35 offset:40032
	ds_write_b16_d16_hi v173, v35 offset:40560
	ds_write_b16 v174, v36 offset:36864
	ds_write_b16_d16_hi v174, v36 offset:37392
	ds_write_b16 v174, v37 offset:37920
	ds_write_b16_d16_hi v174, v37 offset:38448
	ds_write_b16 v174, v38 offset:38976
	ds_write_b16_d16_hi v174, v38 offset:39504
	ds_write_b16 v174, v39 offset:40032
	ds_write_b16_d16_hi v174, v39 offset:40560
	ds_write_b16 v175, v4 offset:36864
	ds_write_b16_d16_hi v175, v4 offset:37392
	ds_write_b16 v175, v5 offset:37920
	ds_write_b16_d16_hi v175, v5 offset:38448
	ds_write_b16 v175, v6 offset:38976
	ds_write_b16_d16_hi v175, v6 offset:39504
	ds_write_b16 v175, v7 offset:40032
	ds_write_b16_d16_hi v175, v7 offset:40560
	v_mov_b32_e32 v4, s0
	v_readlane_b32 s0, v254, 25
	s_waitcnt lgkmcnt(0)
	s_barrier
	s_getreg_b32 s98, hwreg(HW_REG_HW_ID, 0, 4)
	s_cmp_eq_u32 s98, 0
	s_cbranch_scc1 .Lstag_skip
	s_sleep 10
.Lstag_skip:
	v_readlane_b32 s1, v254, 26
	v_and_b32_e32 v5, 64, v237
	v_add_u32_e32 v5, 64, v5
	v_readlane_b32 s48, v254, 41
	v_readlane_b32 s49, v254, 42
	v_readlane_b32 s56, v254, 43
	global_load_dword v188, v4, s[0:1]
	v_xor_b32_e32 v4, 32, v237
	v_cmp_lt_i32_e32 vcc, v4, v5
	s_and_b64 s[86:87], s[16:17], s[48:49]
	v_readlane_b32 s57, v254, 44
	v_cndmask_b32_e32 v4, v237, v4, vcc
	v_lshlrev_b32_e32 v189, 2, v4
	ds_read_b128 v[4:7], v176
	ds_read_b128 v[8:11], v176 offset:32
	s_waitcnt lgkmcnt(1)
	v_mfma_f32_32x32x16_bf16 v[64:79], v[4:7], v[0:3], 0
	ds_read_b128 v[4:7], v176 offset:64
	v_readlane_b32 s38, v254, 45
	s_and_b64 s[88:89], s[16:17], s[56:57]
	v_readlane_b32 s39, v254, 46
	v_readlane_b32 s2, v254, 47
	s_and_b64 s[90:91], s[16:17], s[38:39]
	v_readlane_b32 s3, v254, 48
	s_waitcnt lgkmcnt(1)
	v_mfma_f32_32x32x16_bf16 v[64:79], v[8:11], v[128:131], v[64:79]
	v_readlane_b32 s40, v254, 49
	v_readlane_b32 s52, v254, 37
	s_and_b64 s[92:93], s[16:17], s[2:3]
	v_readlane_b32 s41, v254, 50
	v_readlane_b32 s42, v254, 51
	v_readlane_b32 s53, v254, 38
	v_readlane_b32 s0, v254, 39
	s_waitcnt lgkmcnt(0)
	v_mfma_f32_32x32x16_bf16 v[64:79], v[4:7], v[124:127], v[64:79]
	ds_read_b128 v[4:7], v176 offset:96
	s_and_b64 s[94:95], s[16:17], s[40:41]
	v_readlane_b32 s43, v254, 52
	v_readlane_b32 s44, v254, 53
	s_and_b64 s[82:83], s[16:17], s[52:53]
	v_readlane_b32 s1, v254, 40
	s_and_b64 s[96:97], s[16:17], s[42:43]
	s_waitcnt lgkmcnt(0)
	v_mfma_f32_32x32x16_bf16 v[64:79], v[4:7], v[120:123], v[64:79]
	ds_read_b128 v[4:7], v177
	ds_read_b128 v[8:11], v177 offset:32
	v_readlane_b32 s45, v254, 54
	v_readlane_b32 s68, v254, 55
	s_and_b64 s[84:85], s[16:17], s[0:1]
	s_and_b64 s[28:29], s[16:17], s[44:45]
	v_readlane_b32 s69, v254, 56
	v_readlane_b32 s70, v254, 57
	s_waitcnt lgkmcnt(1)
	v_mfma_f32_32x32x16_bf16 v[48:63], v[4:7], v[0:3], 0
	ds_read_b128 v[4:7], v177 offset:64
	s_nop 0
	v_mul_f32_e32 v66, 0x3e38aa3b, v66
	v_mul_f32_e32 v64, 0x3e38aa3b, v64
	v_cndmask_b32_e64 v80, v239, v64, s[82:83]
	v_mul_f32_e32 v64, 0x3e38aa3b, v65
	v_cndmask_b32_e64 v65, v239, v64, s[84:85]
	s_and_b64 s[4:5], s[16:17], s[68:69]
	s_waitcnt lgkmcnt(1)
	v_mfma_f32_32x32x16_bf16 v[48:63], v[8:11], v[128:131], v[48:63]
	v_readlane_b32 s71, v254, 58
	v_readlane_b32 s72, v254, 59
	s_and_b64 s[6:7], s[16:17], s[70:71]
	v_readlane_b32 s73, v254, 60
	v_readlane_b32 s74, v254, 61
	s_and_b64 s[8:9], s[16:17], s[72:73]
	v_readlane_b32 s75, v254, 62
	s_waitcnt lgkmcnt(0)
	v_mfma_f32_32x32x16_bf16 v[48:63], v[4:7], v[124:127], v[48:63]
	ds_read_b128 v[4:7], v177 offset:96
	v_readlane_b32 s76, v254, 63
	s_and_b64 s[10:11], s[16:17], s[74:75]
	v_readlane_b32 s77, v255, 0
	v_readlane_b32 s78, v255, 1
	s_and_b64 s[12:13], s[16:17], s[76:77]
	v_readlane_b32 s79, v255, 2
	s_waitcnt lgkmcnt(0)
	v_mfma_f32_32x32x16_bf16 v[48:63], v[4:7], v[120:123], v[48:63]
	ds_read_b128 v[4:7], v178
	ds_read_b128 v[8:11], v178 offset:32
	v_readlane_b32 s36, v255, 3
	s_and_b64 s[14:15], s[16:17], s[78:79]
	v_readlane_b32 s37, v255, 4
	s_and_b64 s[18:19], s[16:17], s[36:37]
	v_readlane_b32 s80, v252, 57
	v_readlane_b32 s81, v252, 58
	s_waitcnt lgkmcnt(1)
	v_mfma_f32_32x32x16_bf16 v[32:47], v[4:7], v[0:3], 0
	ds_read_b128 v[4:7], v178 offset:64
	s_nop 0
	v_mul_f32_e32 v48, 0x3e38aa3b, v48
	s_waitcnt vmcnt(0)
	v_mul_f32_e32 v190, 0x3fb8aa3b, v188
	v_max3_f32 v64, v190, v80, v65
	v_readlane_b32 s0, v255, 5
	v_readlane_b32 s1, v255, 6
	s_add_i32 s31, s31, 1
	s_waitcnt lgkmcnt(1)
	v_mfma_f32_32x32x16_bf16 v[32:47], v[8:11], v[128:131], v[32:47]
	s_add_i32 s51, s51, 32
	s_waitcnt lgkmcnt(0)
	v_mfma_f32_32x32x16_bf16 v[32:47], v[4:7], v[124:127], v[32:47]
	ds_read_b128 v[4:7], v178 offset:96
	s_waitcnt lgkmcnt(0)
	v_mfma_f32_32x32x16_bf16 v[32:47], v[4:7], v[120:123], v[32:47]
	ds_read_b128 v[4:7], v179
	ds_read_b128 v[8:11], v179 offset:32
	s_waitcnt lgkmcnt(1)
	v_mfma_f32_32x32x16_bf16 v[16:31], v[4:7], v[0:3], 0
	ds_read_b128 v[4:7], v179 offset:64
	s_nop 6
	v_mul_f32_e32 v32, 0x3e38aa3b, v32
	s_waitcnt lgkmcnt(1)
	v_mfma_f32_32x32x16_bf16 v[16:31], v[8:11], v[128:131], v[16:31]
	s_waitcnt lgkmcnt(0)
	v_mfma_f32_32x32x16_bf16 v[16:31], v[4:7], v[124:127], v[16:31]
	ds_read_b128 v[4:7], v179 offset:96
	s_waitcnt lgkmcnt(0)
	v_mfma_f32_32x32x16_bf16 v[16:31], v[4:7], v[120:123], v[16:31]
	ds_read_b128 v[4:7], v180
	ds_read_b128 v[192:195], v180 offset:32
	s_waitcnt lgkmcnt(1)
	v_mfma_f32_32x32x16_bf16 v[0:15], v[4:7], v[0:3], 0
	s_nop 7
	v_mul_f32_e32 v16, 0x3e38aa3b, v16
	s_waitcnt lgkmcnt(0)
	v_mfma_f32_32x32x16_bf16 v[0:15], v[192:195], v[128:131], v[0:15]
	ds_read_b128 v[128:131], v180 offset:64
	s_waitcnt lgkmcnt(0)
	v_mfma_f32_32x32x16_bf16 v[0:15], v[128:131], v[124:127], v[0:15]
	ds_read_b128 v[124:127], v180 offset:96
	v_cndmask_b32_e64 v131, v239, v48, s[16:17]
	v_mul_f32_e32 v48, 0x3e38aa3b, v49
	v_mul_f32_e32 v49, 0x3e38aa3b, v50
	v_cndmask_b32_e64 v50, v239, v49, s[16:17]
	v_mul_f32_e32 v49, 0x3e38aa3b, v51
	v_cndmask_b32_e64 v51, v239, v49, s[16:17]
	s_waitcnt lgkmcnt(0)
	v_mfma_f32_32x32x16_bf16 v[0:15], v[124:127], v[120:123], v[0:15]
	v_cndmask_b32_e64 v120, v239, v66, s[86:87]
	v_mul_f32_e32 v66, 0x3e38aa3b, v67
	v_cndmask_b32_e64 v67, v239, v66, s[88:89]
	v_mul_f32_e32 v66, 0x3e38aa3b, v68
	v_cndmask_b32_e64 v121, v239, v66, s[90:91]
	v_mul_f32_e32 v66, 0x3e38aa3b, v69
	v_mul_f32_e32 v49, 0x3e38aa3b, v52
	v_cndmask_b32_e64 v69, v239, v66, s[92:93]
	v_mul_f32_e32 v66, 0x3e38aa3b, v70
	v_cndmask_b32_e64 v52, v239, v49, s[16:17]
	v_mul_f32_e32 v49, 0x3e38aa3b, v53
	v_cndmask_b32_e64 v70, v239, v66, s[94:95]
	v_mul_f32_e32 v66, 0x3e38aa3b, v71
	v_cndmask_b32_e64 v53, v239, v49, s[16:17]
	v_mul_f32_e32 v49, 0x3e38aa3b, v54
	v_cndmask_b32_e64 v71, v239, v66, s[96:97]
	v_mul_f32_e32 v66, 0x3e38aa3b, v72
	v_cndmask_b32_e64 v54, v239, v49, s[16:17]
	v_mul_f32_e32 v49, 0x3e38aa3b, v55
	v_cndmask_b32_e64 v72, v239, v66, s[28:29]
	v_mul_f32_e32 v66, 0x3e38aa3b, v73
	v_cndmask_b32_e64 v192, v239, v49, s[16:17]
	v_mul_f32_e32 v49, 0x3e38aa3b, v56
	v_cndmask_b32_e64 v126, v239, v66, s[4:5]
	v_mul_f32_e32 v66, 0x3e38aa3b, v74
	v_cndmask_b32_e64 v193, v239, v49, s[16:17]
	v_mul_f32_e32 v49, 0x3e38aa3b, v57
	v_max3_f32 v64, v64, v120, v67
	v_cndmask_b32_e64 v127, v239, v66, s[6:7]
	v_mul_f32_e32 v66, 0x3e38aa3b, v75
	v_cndmask_b32_e64 v194, v239, v49, s[16:17]
	v_mul_f32_e32 v49, 0x3e38aa3b, v58
	v_max3_f32 v64, v64, v121, v69
	v_cndmask_b32_e64 v75, v239, v66, s[8:9]
	v_mul_f32_e32 v66, 0x3e38aa3b, v76
	v_cndmask_b32_e64 v58, v239, v49, s[16:17]
	v_mul_f32_e32 v49, 0x3e38aa3b, v59
	v_max3_f32 v64, v64, v70, v71
	v_cndmask_b32_e64 v128, v239, v66, s[10:11]
	v_mul_f32_e32 v66, 0x3e38aa3b, v77
	v_cndmask_b32_e64 v195, v239, v49, s[16:17]
	v_mul_f32_e32 v49, 0x3e38aa3b, v60
	v_max3_f32 v64, v64, v72, v126
	v_cndmask_b32_e64 v77, v239, v66, s[12:13]
	v_mul_f32_e32 v66, 0x3e38aa3b, v78
	v_cndmask_b32_e64 v196, v239, v49, s[16:17]
	v_mul_f32_e32 v49, 0x3e38aa3b, v61
	v_max3_f32 v64, v64, v127, v75
	v_cndmask_b32_e64 v129, v239, v66, s[14:15]
	v_mul_f32_e32 v66, 0x3e38aa3b, v79
	v_cndmask_b32_e64 v197, v239, v49, s[16:17]
	v_mul_f32_e32 v49, 0x3e38aa3b, v62
	v_max3_f32 v64, v64, v128, v77
	v_cndmask_b32_e64 v130, v239, v66, s[18:19]
	v_cndmask_b32_e64 v198, v239, v49, s[16:17]
	v_mul_f32_e32 v49, 0x3e38aa3b, v63
	v_max3_f32 v64, v64, v129, v130
	v_cndmask_b32_e64 v191, v239, v48, s[16:17]
	v_cndmask_b32_e64 v199, v239, v49, s[16:17]
	s_or_b64 s[16:17], s[16:17], s[80:81]
	v_max3_f32 v48, v64, v131, v191
	v_cndmask_b32_e64 v200, v239, v32, s[16:17]
	v_mul_f32_e32 v32, 0x3e38aa3b, v33
	v_mul_f32_e32 v33, 0x3e38aa3b, v34
	v_max3_f32 v48, v48, v50, v51
	v_cndmask_b32_e64 v202, v239, v33, s[16:17]
	v_mul_f32_e32 v33, 0x3e38aa3b, v35
	v_max3_f32 v48, v48, v52, v53
	v_cndmask_b32_e64 v203, v239, v33, s[16:17]
	v_mul_f32_e32 v33, 0x3e38aa3b, v36
	v_max3_f32 v48, v48, v54, v192
	v_cndmask_b32_e64 v204, v239, v33, s[16:17]
	v_mul_f32_e32 v33, 0x3e38aa3b, v37
	v_max3_f32 v48, v48, v193, v194
	v_cndmask_b32_e64 v205, v239, v33, s[16:17]
	v_mul_f32_e32 v33, 0x3e38aa3b, v38
	v_max3_f32 v48, v48, v58, v195
	v_cndmask_b32_e64 v206, v239, v33, s[16:17]
	v_mul_f32_e32 v33, 0x3e38aa3b, v39
	v_cndmask_b32_e64 v74, v239, v16, s[16:17]
	v_mul_f32_e32 v16, 0x3e38aa3b, v17
	v_mul_f32_e32 v17, 0x3e38aa3b, v18
	v_max3_f32 v48, v48, v196, v197
	v_cndmask_b32_e64 v207, v239, v33, s[16:17]
	v_mul_f32_e32 v33, 0x3e38aa3b, v40
	v_cndmask_b32_e64 v68, v239, v17, s[16:17]
	v_mul_f32_e32 v17, 0x3e38aa3b, v19
	v_max3_f32 v48, v48, v198, v199
	v_cndmask_b32_e64 v201, v239, v32, s[16:17]
	v_cndmask_b32_e64 v208, v239, v33, s[16:17]
	v_mul_f32_e32 v33, 0x3e38aa3b, v41
	v_cndmask_b32_e64 v66, v239, v17, s[16:17]
	v_mul_f32_e32 v17, 0x3e38aa3b, v20
	v_max3_f32 v32, v48, v200, v201
	v_cndmask_b32_e64 v125, v239, v33, s[16:17]
	v_mul_f32_e32 v33, 0x3e38aa3b, v42
	v_cndmask_b32_e64 v64, v239, v17, s[16:17]
	v_mul_f32_e32 v17, 0x3e38aa3b, v21
	v_max3_f32 v32, v32, v202, v203
	v_cndmask_b32_e64 v124, v239, v33, s[16:17]
	v_mul_f32_e32 v33, 0x3e38aa3b, v43
	v_cndmask_b32_e64 v62, v239, v17, s[16:17]
	v_mul_f32_e32 v17, 0x3e38aa3b, v22
	v_max3_f32 v32, v32, v204, v205
	v_cndmask_b32_e64 v123, v239, v33, s[16:17]
	v_mul_f32_e32 v33, 0x3e38aa3b, v44
	v_cndmask_b32_e64 v60, v239, v17, s[16:17]
	v_mul_f32_e32 v17, 0x3e38aa3b, v23
	v_max3_f32 v32, v32, v206, v207
	v_cndmask_b32_e64 v122, v239, v33, s[16:17]
	v_mul_f32_e32 v33, 0x3e38aa3b, v45
	v_cndmask_b32_e64 v57, v239, v17, s[16:17]
	v_mul_f32_e32 v17, 0x3e38aa3b, v24
	v_max3_f32 v32, v32, v208, v125
	v_cndmask_b32_e64 v79, v239, v33, s[16:17]
	v_mul_f32_e32 v33, 0x3e38aa3b, v46
	v_cndmask_b32_e64 v59, v239, v17, s[16:17]
	v_mul_f32_e32 v17, 0x3e38aa3b, v25
	v_max3_f32 v32, v32, v124, v123
	v_cndmask_b32_e64 v78, v239, v33, s[16:17]
	v_mul_f32_e32 v33, 0x3e38aa3b, v47
	v_cndmask_b32_e64 v48, v239, v17, s[16:17]
	v_mul_f32_e32 v17, 0x3e38aa3b, v26
	v_max3_f32 v32, v32, v122, v79
	v_cndmask_b32_e64 v76, v239, v33, s[16:17]
	v_cndmask_b32_e64 v55, v239, v17, s[16:17]
	v_mul_f32_e32 v17, 0x3e38aa3b, v27
	v_max3_f32 v32, v32, v78, v76
	v_cndmask_b32_e64 v73, v239, v16, s[16:17]
	v_cndmask_b32_e64 v45, v239, v17, s[16:17]
	v_mul_f32_e32 v17, 0x3e38aa3b, v28
	v_mul_f32_e32 v0, 0x3e38aa3b, v0
	v_max3_f32 v16, v32, v74, v73
	v_cndmask_b32_e64 v46, v239, v17, s[16:17]
	v_mul_f32_e32 v17, 0x3e38aa3b, v29
	v_cndmask_b32_e64 v24, v0, v239, s[52:53]
	v_mul_f32_e32 v0, 0x3e38aa3b, v1
	v_mul_f32_e32 v1, 0x3e38aa3b, v2
	v_max3_f32 v16, v16, v68, v66
	v_cndmask_b32_e64 v27, v239, v17, s[16:17]
	v_mul_f32_e32 v17, 0x3e38aa3b, v30
	v_cndmask_b32_e64 v30, v1, v239, s[48:49]
	v_mul_f32_e32 v1, 0x3e38aa3b, v3
	v_max3_f32 v16, v16, v64, v62
	v_cndmask_b32_e64 v25, v1, v239, s[56:57]
	v_mul_f32_e32 v1, 0x3e38aa3b, v4
	v_max3_f32 v16, v16, v60, v57
	v_cndmask_b32_e64 v26, v1, v239, s[38:39]
	v_mul_f32_e32 v1, 0x3e38aa3b, v5
	v_max3_f32 v16, v16, v59, v48
	v_cndmask_b32_e64 v21, v1, v239, s[2:3]
	v_mul_f32_e32 v1, 0x3e38aa3b, v6
	v_max3_f32 v16, v16, v55, v45
	v_cndmask_b32_e64 v28, v239, v17, s[16:17]
	v_mul_f32_e32 v17, 0x3e38aa3b, v31
	v_cndmask_b32_e64 v22, v1, v239, s[40:41]
	v_mul_f32_e32 v1, 0x3e38aa3b, v7
	v_max3_f32 v16, v16, v46, v27
	v_cndmask_b32_e64 v23, v239, v17, s[16:17]
	v_cndmask_b32_e64 v19, v1, v239, s[42:43]
	v_mul_f32_e32 v1, 0x3e38aa3b, v8
	v_max3_f32 v16, v16, v28, v23
	v_cndmask_b32_e64 v29, v239, v0, s[0:1]
	v_cndmask_b32_e64 v20, v1, v239, s[44:45]
	v_mul_f32_e32 v1, 0x3e38aa3b, v9
	v_max3_f32 v0, v16, v24, v29
	v_cndmask_b32_e64 v17, v1, v239, s[68:69]
	v_mul_f32_e32 v1, 0x3e38aa3b, v10
	v_max3_f32 v0, v0, v30, v25
	v_cndmask_b32_e64 v18, v1, v239, s[70:71]
	v_mul_f32_e32 v1, 0x3e38aa3b, v11
	v_max3_f32 v0, v0, v26, v21
	v_cndmask_b32_e64 v16, v1, v239, s[72:73]
	v_mul_f32_e32 v1, 0x3e38aa3b, v12
	v_max3_f32 v0, v0, v22, v19
	v_cndmask_b32_e64 v12, v1, v239, s[74:75]
	v_mul_f32_e32 v1, 0x3e38aa3b, v13
	v_max3_f32 v0, v0, v20, v17
	v_cndmask_b32_e64 v10, v1, v239, s[76:77]
	v_mul_f32_e32 v1, 0x3e38aa3b, v14
	v_max3_f32 v0, v0, v18, v16
	v_cndmask_b32_e64 v11, v1, v239, s[78:79]
	v_mul_f32_e32 v1, 0x3e38aa3b, v15
	v_max3_f32 v0, v0, v12, v10
	v_cndmask_b32_e64 v9, v1, v239, s[36:37]
	v_max3_f32 v0, v0, v11, v9
	ds_bpermute_b32 v1, v189, v0
	s_mov_b32 s80, 0x3fb8aa3b
	s_waitcnt lgkmcnt(0)
	v_max_f32_e32 v1, v1, v1
	v_max_f32_e32 v8, v0, v1
	v_sub_f32_e32 v0, v80, v8
	v_exp_f32_e32 v0, v0
	v_sub_f32_e32 v1, v65, v8
	v_exp_f32_e32 v1, v1
	v_sub_f32_e32 v14, v72, v8
	v_add_f32_e32 v2, 0, v0
	v_exp_f32_e32 v32, v14
	v_add_f32_e32 v3, v2, v1
	v_sub_f32_e32 v2, v120, v8
	v_exp_f32_e32 v2, v2
	v_sub_f32_e32 v14, v126, v8
	v_exp_f32_e32 v33, v14
	v_sub_f32_e32 v14, v127, v8
	v_add_f32_e32 v4, v3, v2
	v_sub_f32_e32 v3, v67, v8
	v_exp_f32_e32 v3, v3
	v_exp_f32_e32 v34, v14
	v_sub_f32_e32 v14, v75, v8
	v_exp_f32_e32 v36, v14
	v_add_f32_e32 v5, v4, v3
	v_sub_f32_e32 v4, v121, v8
	v_exp_f32_e32 v4, v4
	v_sub_f32_e32 v14, v128, v8
	v_exp_f32_e32 v38, v14
	v_sub_f32_e32 v14, v77, v8
	v_add_f32_e32 v6, v5, v4
	v_sub_f32_e32 v5, v69, v8
	v_exp_f32_e32 v5, v5
	v_exp_f32_e32 v39, v14
	v_sub_f32_e32 v14, v129, v8
	v_exp_f32_e32 v44, v14
	v_add_f32_e32 v7, v6, v5
	v_sub_f32_e32 v6, v70, v8
	v_exp_f32_e32 v6, v6
	v_sub_f32_e32 v14, v130, v8
	v_exp_f32_e32 v49, v14
	v_sub_f32_e32 v14, v131, v8
	v_add_f32_e32 v13, v7, v6
	v_sub_f32_e32 v7, v71, v8
	v_exp_f32_e32 v7, v7
	v_exp_f32_e32 v35, v14
	v_sub_f32_e32 v14, v191, v8
	v_exp_f32_e32 v37, v14
	v_add_f32_e32 v13, v13, v7
	v_add_f32_e32 v13, v13, v32
	v_add_f32_e32 v13, v13, v33
	v_add_f32_e32 v13, v13, v34
	v_add_f32_e32 v13, v13, v36
	v_add_f32_e32 v13, v13, v38
	v_add_f32_e32 v13, v13, v39
	v_sub_f32_e32 v14, v50, v8
	v_add_f32_e32 v13, v13, v44
	v_exp_f32_e32 v40, v14
	v_sub_f32_e32 v14, v51, v8
	v_add_f32_e32 v13, v13, v49
	v_exp_f32_e32 v42, v14
	v_sub_f32_e32 v14, v52, v8
	v_add_f32_e32 v13, v13, v35
	v_exp_f32_e32 v47, v14
	v_sub_f32_e32 v14, v53, v8
	v_add_f32_e32 v13, v13, v37
	v_exp_f32_e32 v50, v14
	v_sub_f32_e32 v14, v54, v8
	v_add_f32_e32 v13, v13, v40
	v_exp_f32_e32 v56, v14
	v_sub_f32_e32 v14, v192, v8
	v_add_f32_e32 v13, v13, v42
	v_exp_f32_e32 v61, v14
	v_sub_f32_e32 v14, v193, v8
	v_add_f32_e32 v13, v13, v47
	v_exp_f32_e32 v41, v14
	v_sub_f32_e32 v14, v194, v8
	v_add_f32_e32 v13, v13, v50
	v_exp_f32_e32 v43, v14
	v_sub_f32_e32 v14, v58, v8
	v_add_f32_e32 v13, v13, v56
	v_exp_f32_e32 v51, v14
	v_sub_f32_e32 v14, v195, v8
	v_add_f32_e32 v13, v13, v61
	v_exp_f32_e32 v53, v14
	v_sub_f32_e32 v14, v196, v8
	v_add_f32_e32 v13, v13, v41
	v_exp_f32_e32 v58, v14
	v_sub_f32_e32 v14, v197, v8
	v_add_f32_e32 v13, v13, v43
	v_exp_f32_e32 v63, v14
	v_sub_f32_e32 v14, v198, v8
	v_add_f32_e32 v13, v13, v51
	v_exp_f32_e32 v71, v14
	v_sub_f32_e32 v14, v199, v8
	v_add_f32_e32 v13, v13, v53
	v_exp_f32_e32 v75, v14
	v_sub_f32_e32 v14, v200, v8
	v_add_f32_e32 v13, v13, v58
	v_exp_f32_e32 v52, v14
	v_sub_f32_e32 v14, v201, v8
	v_add_f32_e32 v13, v13, v63
	v_exp_f32_e32 v54, v14
	v_sub_f32_e32 v14, v202, v8
	v_add_f32_e32 v13, v13, v71
	v_exp_f32_e32 v65, v14
	v_sub_f32_e32 v14, v203, v8
	v_add_f32_e32 v13, v13, v75
	v_exp_f32_e32 v69, v14
	v_sub_f32_e32 v14, v204, v8
	v_add_f32_e32 v13, v13, v52
	v_exp_f32_e32 v72, v14
	v_sub_f32_e32 v14, v205, v8
	v_add_f32_e32 v13, v13, v54
	v_exp_f32_e32 v77, v14
	v_sub_f32_e32 v14, v206, v8
	v_add_f32_e32 v13, v13, v65
	v_exp_f32_e32 v126, v14
	v_sub_f32_e32 v14, v207, v8
	v_add_f32_e32 v13, v13, v69
	v_exp_f32_e32 v129, v14
	v_sub_f32_e32 v14, v208, v8
	v_add_f32_e32 v13, v13, v72
	v_exp_f32_e32 v67, v14
	v_sub_f32_e32 v14, v125, v8
	v_add_f32_e32 v13, v13, v77
	v_exp_f32_e32 v70, v14
	v_sub_f32_e32 v14, v124, v8
	v_add_f32_e32 v13, v13, v126
	v_exp_f32_e32 v80, v14
	v_sub_f32_e32 v14, v123, v8
	v_add_f32_e32 v13, v13, v129
	v_exp_f32_e32 v124, v14
	v_sub_f32_e32 v14, v122, v8
	v_add_f32_e32 v13, v13, v67
	v_exp_f32_e32 v127, v14
	v_sub_f32_e32 v14, v79, v8
	v_add_f32_e32 v13, v13, v70
	v_exp_f32_e32 v131, v14
	v_sub_f32_e32 v14, v78, v8
	v_add_f32_e32 v13, v13, v80
	v_exp_f32_e32 v199, v14
	v_sub_f32_e32 v14, v76, v8
	v_add_f32_e32 v13, v13, v124
	v_exp_f32_e32 v201, v14
	v_sub_f32_e32 v14, v74, v8
	v_add_f32_e32 v13, v13, v127
	v_exp_f32_e32 v121, v14
	v_sub_f32_e32 v14, v73, v8
	v_add_f32_e32 v13, v13, v131
	v_exp_f32_e32 v125, v14
	v_sub_f32_e32 v14, v68, v8
	v_add_f32_e32 v13, v13, v199
	v_exp_f32_e32 v192, v14
	v_sub_f32_e32 v14, v66, v8
	v_add_f32_e32 v13, v13, v201
	v_exp_f32_e32 v196, v14
	v_sub_f32_e32 v14, v64, v8
	v_add_f32_e32 v13, v13, v121
	v_exp_f32_e32 v200, v14
	v_sub_f32_e32 v14, v62, v8
	v_add_f32_e32 v13, v13, v125
	v_exp_f32_e32 v202, v14
	v_sub_f32_e32 v14, v60, v8
	v_add_f32_e32 v13, v13, v192
	v_exp_f32_e32 v203, v14
	v_sub_f32_e32 v14, v57, v8
	v_add_f32_e32 v13, v13, v196
	v_exp_f32_e32 v204, v14
	v_sub_f32_e32 v14, v59, v8
	v_add_f32_e32 v13, v13, v200
	v_exp_f32_e32 v128, v14
	v_sub_f32_e32 v14, v48, v8
	v_add_f32_e32 v13, v13, v202
	v_exp_f32_e32 v130, v14
	v_sub_f32_e32 v14, v55, v8
	v_add_f32_e32 v13, v13, v203
	v_exp_f32_e32 v191, v14
	v_sub_f32_e32 v14, v45, v8
	v_add_f32_e32 v13, v13, v204
	v_exp_f32_e32 v193, v14
	v_sub_f32_e32 v14, v46, v8
	v_add_f32_e32 v13, v13, v128
	v_exp_f32_e32 v194, v14
	v_sub_f32_e32 v14, v27, v8
	v_add_f32_e32 v13, v13, v130
	v_exp_f32_e32 v195, v14
	v_sub_f32_e32 v14, v28, v8
	v_add_f32_e32 v13, v13, v191
	v_exp_f32_e32 v197, v14
	v_sub_f32_e32 v14, v23, v8
	v_add_f32_e32 v13, v13, v193
	v_exp_f32_e32 v198, v14
	v_sub_f32_e32 v14, v24, v8
	v_add_f32_e32 v13, v13, v194
	v_exp_f32_e32 v73, v14
	v_sub_f32_e32 v14, v29, v8
	v_add_f32_e32 v13, v13, v195
	v_exp_f32_e32 v74, v14
	v_sub_f32_e32 v14, v30, v8
	v_add_f32_e32 v13, v13, v197
	v_exp_f32_e32 v76, v14
	v_sub_f32_e32 v14, v25, v8
	v_add_f32_e32 v13, v13, v198
	v_exp_f32_e32 v78, v14
	v_sub_f32_e32 v14, v26, v8
	v_add_f32_e32 v13, v13, v73
	v_exp_f32_e32 v79, v14
	v_sub_f32_e32 v14, v21, v8
	v_add_f32_e32 v13, v13, v74
	v_exp_f32_e32 v120, v14
	v_sub_f32_e32 v14, v22, v8
	v_add_f32_e32 v13, v13, v76
	v_exp_f32_e32 v122, v14
	v_sub_f32_e32 v14, v19, v8
	v_add_f32_e32 v13, v13, v78
	v_exp_f32_e32 v123, v14
	v_sub_f32_e32 v14, v20, v8
	v_add_f32_e32 v13, v13, v79
	v_exp_f32_e32 v55, v14
	v_sub_f32_e32 v14, v17, v8
	v_add_f32_e32 v13, v13, v120
	v_exp_f32_e32 v57, v14
	v_sub_f32_e32 v14, v18, v8
	v_add_f32_e32 v13, v13, v122
	v_exp_f32_e32 v59, v14
	v_sub_f32_e32 v14, v16, v8
	v_add_f32_e32 v13, v13, v123
	v_exp_f32_e32 v60, v14
	v_sub_f32_e32 v12, v12, v8
	v_add_f32_e32 v13, v13, v55
	v_exp_f32_e32 v62, v12
	v_sub_f32_e32 v10, v10, v8
	v_add_f32_e32 v13, v13, v57
	v_exp_f32_e32 v64, v10
	v_sub_f32_e32 v11, v11, v8
	v_add_f32_e32 v13, v13, v59
	v_exp_f32_e32 v66, v11
	v_sub_f32_e32 v9, v9, v8
	v_add_f32_e32 v13, v13, v60
	v_exp_f32_e32 v68, v9
	v_add_f32_e32 v12, v13, v62
	v_add_f32_e32 v10, v12, v64
	v_add_f32_e32 v10, v10, v66
	v_fma_f32 v8, v188, s80, -v8
	v_add_f32_e32 v45, v10, v68
	v_exp_f32_e32 v48, v8
	v_cvt_pk_bf16_f32 v0, v0, v1
	v_cvt_pk_bf16_f32 v1, v2, v3
	v_cvt_pk_bf16_f32 v2, v4, v5
	v_cvt_pk_bf16_f32 v3, v6, v7
	ds_read_b128 v[4:7], v181 offset:36864
	ds_read_b128 v[8:11], v181 offset:53760
	s_waitcnt lgkmcnt(1)
	v_mfma_f32_32x32x16_bf16 v[16:31], v[4:7], v[0:3], 0
	v_cvt_pk_bf16_f32 v220, v32, v33
	v_cvt_pk_bf16_f32 v221, v34, v36
	v_cvt_pk_bf16_f32 v222, v38, v39
	v_cvt_pk_bf16_f32 v223, v44, v49
	ds_read_b128 v[224:227], v181 offset:36896
	ds_read_b128 v[228:231], v181 offset:53792
	v_cvt_pk_bf16_f32 v32, v35, v37
	v_cvt_pk_bf16_f32 v33, v40, v42
	s_waitcnt lgkmcnt(2)
	v_mfma_f32_32x32x16_bf16 v[0:15], v[8:11], v[0:3], 0
	v_cvt_pk_bf16_f32 v34, v47, v50
	v_cvt_pk_bf16_f32 v35, v56, v61
	ds_bpermute_b32 v46, v189, v45
	s_waitcnt lgkmcnt(2)
	v_mfma_f32_32x32x16_bf16 v[16:31], v[224:227], v[220:223], v[16:31]
	s_waitcnt lgkmcnt(1)
	v_mfma_f32_32x32x16_bf16 v[0:15], v[228:231], v[220:223], v[0:15]
	ds_read_b128 v[84:87], v182 offset:36864
	ds_read_b128 v[88:91], v182 offset:53760
	ds_read_b128 v[92:95], v182 offset:36896
	ds_read_b128 v[96:99], v182 offset:53792
	s_waitcnt lgkmcnt(3)
	v_mfma_f32_32x32x16_bf16 v[16:31], v[84:87], v[32:35], v[16:31]
	s_waitcnt lgkmcnt(2)
	v_mfma_f32_32x32x16_bf16 v[0:15], v[88:91], v[32:35], v[0:15]
	v_cvt_pk_bf16_f32 v32, v41, v43
	v_cvt_pk_bf16_f32 v33, v51, v53
	v_cvt_pk_bf16_f32 v34, v58, v63
	v_cvt_pk_bf16_f32 v35, v71, v75
	ds_read_b128 v[84:87], v183 offset:36864
	ds_read_b128 v[88:91], v183 offset:53760
	s_waitcnt lgkmcnt(3)
	v_mfma_f32_32x32x16_bf16 v[16:31], v[92:95], v[32:35], v[16:31]
	s_waitcnt lgkmcnt(2)
	v_mfma_f32_32x32x16_bf16 v[0:15], v[96:99], v[32:35], v[0:15]
	v_cvt_pk_bf16_f32 v32, v52, v54
	v_cvt_pk_bf16_f32 v33, v65, v69
	v_cvt_pk_bf16_f32 v34, v72, v77
	v_cvt_pk_bf16_f32 v35, v126, v129
	ds_read_b128 v[92:95], v183 offset:36896
	ds_read_b128 v[96:99], v183 offset:53792
	s_waitcnt lgkmcnt(3)
	v_mfma_f32_32x32x16_bf16 v[16:31], v[84:87], v[32:35], v[16:31]
	s_waitcnt lgkmcnt(2)
	v_mfma_f32_32x32x16_bf16 v[0:15], v[88:91], v[32:35], v[0:15]
	v_cvt_pk_bf16_f32 v32, v67, v70
	v_cvt_pk_bf16_f32 v33, v80, v124
	v_cvt_pk_bf16_f32 v34, v127, v131
	v_cvt_pk_bf16_f32 v35, v199, v201
	ds_read_b128 v[84:87], v184 offset:36864
	ds_read_b128 v[88:91], v184 offset:53760
	s_waitcnt lgkmcnt(3)
	v_mfma_f32_32x32x16_bf16 v[16:31], v[92:95], v[32:35], v[16:31]
	s_waitcnt lgkmcnt(2)
	v_mfma_f32_32x32x16_bf16 v[0:15], v[96:99], v[32:35], v[0:15]
	v_cvt_pk_bf16_f32 v32, v121, v125
	v_cvt_pk_bf16_f32 v33, v192, v196
	v_cvt_pk_bf16_f32 v34, v200, v202
	v_cvt_pk_bf16_f32 v35, v203, v204
	ds_read_b128 v[92:95], v184 offset:36896
	ds_read_b128 v[96:99], v184 offset:53792
	s_waitcnt lgkmcnt(3)
	v_mfma_f32_32x32x16_bf16 v[16:31], v[84:87], v[32:35], v[16:31]
	s_waitcnt lgkmcnt(2)
	v_mfma_f32_32x32x16_bf16 v[0:15], v[88:91], v[32:35], v[0:15]
	v_cvt_pk_bf16_f32 v32, v128, v130
	v_cvt_pk_bf16_f32 v33, v191, v193
	v_cvt_pk_bf16_f32 v34, v194, v195
	v_cvt_pk_bf16_f32 v35, v197, v198
	ds_read_b128 v[84:87], v185 offset:36864
	ds_read_b128 v[88:91], v185 offset:53760
	s_waitcnt lgkmcnt(3)
	v_mfma_f32_32x32x16_bf16 v[16:31], v[92:95], v[32:35], v[16:31]
	s_waitcnt lgkmcnt(2)
	v_mfma_f32_32x32x16_bf16 v[0:15], v[96:99], v[32:35], v[0:15]
	v_cvt_pk_bf16_f32 v32, v73, v74
	v_cvt_pk_bf16_f32 v33, v76, v78
	v_cvt_pk_bf16_f32 v34, v79, v120
	v_cvt_pk_bf16_f32 v35, v122, v123
	ds_read_b128 v[92:95], v185 offset:36896
	ds_read_b128 v[96:99], v185 offset:53792
	s_waitcnt lgkmcnt(3)
	v_mfma_f32_32x32x16_bf16 v[16:31], v[84:87], v[32:35], v[16:31]
	s_waitcnt lgkmcnt(2)
	v_mfma_f32_32x32x16_bf16 v[0:15], v[88:91], v[32:35], v[0:15]
	v_cvt_pk_bf16_f32 v32, v55, v57
	v_cvt_pk_bf16_f32 v33, v59, v60
	v_cvt_pk_bf16_f32 v34, v62, v64
	v_cvt_pk_bf16_f32 v35, v66, v68
	s_waitcnt lgkmcnt(1)
	v_mfma_f32_32x32x16_bf16 v[16:31], v[92:95], v[32:35], v[16:31]
	s_waitcnt lgkmcnt(0)
	v_mfma_f32_32x32x16_bf16 v[0:15], v[96:99], v[32:35], v[0:15]
	v_add_f32_e32 v32, v45, v46
	v_add_f32_e32 v32, v48, v32
	v_div_scale_f32 v33, s[80:81], v32, v32, 1.0
	v_rcp_f32_e32 v34, v33
	v_readlane_b32 s80, v253, 57
	v_readlane_b32 s81, v253, 58
	v_fma_f32 v35, -v33, v34, 1.0
	v_fmac_f32_e32 v34, v35, v34
	v_div_scale_f32 v35, vcc, 1.0, v32, 1.0
	v_mul_f32_e32 v36, v35, v34
	v_fma_f32 v37, -v33, v36, v35
	v_fmac_f32_e32 v36, v37, v34
	v_fma_f32 v33, -v33, v36, v35
	v_div_fmas_f32 v33, v33, v34, v36
	v_div_fixup_f32 v34, v33, v32, 1.0
	v_lshrrev_b64 v[32:33], 2, v[162:163]
	v_and_b32_e32 v33, 0x3ffff, v33
	v_and_b32_e32 v32, 0xffffffe0, v32
	v_lshlrev_b32_e32 v35, 6, v162
	v_lshlrev_b32_e32 v37, 2, v162
	v_lshl_add_u64 v[32:33], v[32:33], 0, s[34:35]
	v_and_b32_e32 v35, 0x3c0, v35
	v_lshlrev_b32_e32 v36, 7, v162
	v_and_b32_e32 v37, 32, v37
	v_and_b32_e32 v36, 0x3800, v36
	v_lshlrev_b64 v[32:33], 14, v[32:33]
	v_mul_f32_e32 v16, v34, v16
	v_mul_f32_e32 v17, v34, v17
	v_or3_b32 v39, v137, v35, v37
	v_lshl_add_u64 v[32:33], s[80:81], 0, v[32:33]
	v_cvt_pk_bf16_f32 v16, v16, v17
	v_mul_f32_e32 v17, v34, v18
	v_mul_f32_e32 v18, v34, v19
	v_or_b32_e32 v80, v39, v36
	v_or_b32_e32 v38, 0x400, v36
	v_cvt_pk_bf16_f32 v17, v17, v18
	v_lshl_add_u64 v[18:19], v[32:33], 0, v[80:81]
	v_mul_f32_e32 v0, v34, v0
	v_mul_f32_e32 v1, v34, v1
	global_store_dwordx2 v[18:19], v[16:17], off
	v_cvt_pk_bf16_f32 v0, v0, v1
	v_mul_f32_e32 v1, v34, v2
	v_mul_f32_e32 v2, v34, v3
	v_or_b32_e32 v80, v39, v38
	v_cvt_pk_bf16_f32 v1, v1, v2
	v_lshl_add_u64 v[2:3], v[32:33], 0, v[80:81]
	global_store_dwordx2 v[2:3], v[0:1], off
	v_mul_f32_e32 v0, v34, v20
	v_mul_f32_e32 v1, v34, v21
	v_or3_b32 v16, v165, v35, v37
	v_cvt_pk_bf16_f32 v0, v0, v1
	v_mul_f32_e32 v1, v34, v22
	v_mul_f32_e32 v2, v34, v23
	v_or_b32_e32 v80, v16, v36
	v_cvt_pk_bf16_f32 v1, v1, v2
	v_lshl_add_u64 v[2:3], v[32:33], 0, v[80:81]
	global_store_dwordx2 v[2:3], v[0:1], off
	v_mul_f32_e32 v0, v34, v4
	v_mul_f32_e32 v1, v34, v5
	v_cvt_pk_bf16_f32 v0, v0, v1
	v_mul_f32_e32 v1, v34, v6
	v_mul_f32_e32 v2, v34, v7
	v_or_b32_e32 v80, v16, v38
	v_cvt_pk_bf16_f32 v1, v1, v2
	v_lshl_add_u64 v[2:3], v[32:33], 0, v[80:81]
	global_store_dwordx2 v[2:3], v[0:1], off
	v_mul_f32_e32 v0, v34, v24
	v_mul_f32_e32 v1, v34, v25
	v_bitop3_b32 v4, v166, v37, v35 bitop3:0x36
	v_cvt_pk_bf16_f32 v0, v0, v1
	v_mul_f32_e32 v1, v34, v26
	v_mul_f32_e32 v2, v34, v27
	v_or_b32_e32 v80, v4, v36
	v_cvt_pk_bf16_f32 v1, v1, v2
	v_lshl_add_u64 v[2:3], v[32:33], 0, v[80:81]
	global_store_dwordx2 v[2:3], v[0:1], off
	v_mul_f32_e32 v0, v34, v8
	v_mul_f32_e32 v1, v34, v9
	v_cvt_pk_bf16_f32 v0, v0, v1
	v_mul_f32_e32 v1, v34, v10
	v_mul_f32_e32 v2, v34, v11
	v_or_b32_e32 v80, v4, v38
	v_cvt_pk_bf16_f32 v1, v1, v2
	v_lshl_add_u64 v[2:3], v[32:33], 0, v[80:81]
	global_store_dwordx2 v[2:3], v[0:1], off
	v_mul_f32_e32 v0, v34, v28
	v_mul_f32_e32 v1, v34, v29
	v_bitop3_b32 v4, v167, v37, v35 bitop3:0x36
	v_cvt_pk_bf16_f32 v0, v0, v1
	v_mul_f32_e32 v1, v34, v30
	v_mul_f32_e32 v2, v34, v31
	v_or_b32_e32 v80, v4, v36
	v_cvt_pk_bf16_f32 v1, v1, v2
	v_lshl_add_u64 v[2:3], v[32:33], 0, v[80:81]
	global_store_dwordx2 v[2:3], v[0:1], off
	v_mul_f32_e32 v0, v34, v12
	v_mul_f32_e32 v1, v34, v13
	v_cvt_pk_bf16_f32 v0, v0, v1
	v_mul_f32_e32 v1, v34, v14
	v_mul_f32_e32 v2, v34, v15
	v_or_b32_e32 v80, v4, v38
	v_cvt_pk_bf16_f32 v1, v1, v2
	v_lshl_add_u64 v[2:3], v[32:33], 0, v[80:81]
	global_store_dwordx2 v[2:3], v[0:1], off
	ds_read_b128 v[0:3], v177
	ds_read_b128 v[4:7], v177 offset:32
	s_waitcnt lgkmcnt(1)
	v_mfma_f32_32x32x16_bf16 v[64:79], v[0:3], v[116:119], 0
	ds_read_b128 v[0:3], v177 offset:64
	s_waitcnt lgkmcnt(1)
	v_mfma_f32_32x32x16_bf16 v[64:79], v[4:7], v[112:115], v[64:79]
	s_waitcnt lgkmcnt(0)
	v_mfma_f32_32x32x16_bf16 v[64:79], v[0:3], v[108:111], v[64:79]
	ds_read_b128 v[0:3], v177 offset:96
	s_waitcnt lgkmcnt(0)
	v_mfma_f32_32x32x16_bf16 v[64:79], v[0:3], v[104:107], v[64:79]
	ds_read_b128 v[0:3], v178
	ds_read_b128 v[4:7], v178 offset:32
	s_waitcnt lgkmcnt(1)
	v_mfma_f32_32x32x16_bf16 v[48:63], v[0:3], v[116:119], 0
	ds_read_b128 v[0:3], v178 offset:64
	s_nop 6
	v_mul_f32_e32 v66, 0x3e38aa3b, v66
	v_mul_f32_e32 v64, 0x3e38aa3b, v64
	v_mul_f32_e32 v65, 0x3e38aa3b, v65
	v_cndmask_b32_e64 v64, v239, v64, s[82:83]
	v_cndmask_b32_e64 v80, v239, v65, s[84:85]
	v_max3_f32 v65, v190, v64, v80
	s_waitcnt lgkmcnt(1)
	v_mfma_f32_32x32x16_bf16 v[48:63], v[4:7], v[112:115], v[48:63]
	s_waitcnt lgkmcnt(0)
	v_mfma_f32_32x32x16_bf16 v[48:63], v[0:3], v[108:111], v[48:63]
	ds_read_b128 v[0:3], v178 offset:96
	s_waitcnt lgkmcnt(0)
	v_mfma_f32_32x32x16_bf16 v[48:63], v[0:3], v[104:107], v[48:63]
	ds_read_b128 v[0:3], v179
	ds_read_b128 v[4:7], v179 offset:32
	s_waitcnt lgkmcnt(1)
	v_mfma_f32_32x32x16_bf16 v[32:47], v[0:3], v[116:119], 0
	ds_read_b128 v[0:3], v179 offset:64
	s_nop 6
	v_mul_f32_e32 v48, 0x3e38aa3b, v48
	s_waitcnt lgkmcnt(1)
	v_mfma_f32_32x32x16_bf16 v[32:47], v[4:7], v[112:115], v[32:47]
	s_waitcnt lgkmcnt(0)
	v_mfma_f32_32x32x16_bf16 v[32:47], v[0:3], v[108:111], v[32:47]
	ds_read_b128 v[0:3], v179 offset:96
	s_waitcnt lgkmcnt(0)
	v_mfma_f32_32x32x16_bf16 v[32:47], v[0:3], v[104:107], v[32:47]
	ds_read_b128 v[0:3], v180
	ds_read_b128 v[16:19], v180 offset:32
	s_waitcnt lgkmcnt(1)
	v_mfma_f32_32x32x16_bf16 v[0:15], v[0:3], v[116:119], 0
	s_nop 7
	v_mul_f32_e32 v32, 0x3e38aa3b, v32
	s_waitcnt lgkmcnt(0)
	v_mfma_f32_32x32x16_bf16 v[0:15], v[16:19], v[112:115], v[0:15]
	ds_read_b128 v[16:19], v180 offset:64
	s_waitcnt lgkmcnt(0)
	v_mfma_f32_32x32x16_bf16 v[0:15], v[16:19], v[108:111], v[0:15]
	ds_read_b128 v[16:19], v180 offset:96
	s_waitcnt lgkmcnt(0)
	v_mfma_f32_32x32x16_bf16 v[0:15], v[16:19], v[104:107], v[0:15]
	ds_read_b128 v[16:19], v186
	ds_read_b128 v[120:123], v186 offset:32
	s_waitcnt lgkmcnt(1)
	v_mfma_f32_32x32x16_bf16 v[16:31], v[16:19], v[116:119], 0
	s_waitcnt lgkmcnt(0)
	v_mfma_f32_32x32x16_bf16 v[16:31], v[120:123], v[112:115], v[16:31]
	ds_read_b128 v[112:115], v186 offset:64
	v_cndmask_b32_e64 v122, v239, v32, s[16:17]
	v_mul_f32_e32 v32, 0x3e38aa3b, v33
	v_mul_f32_e32 v33, 0x3e38aa3b, v34
	v_cndmask_b32_e64 v124, v239, v33, s[16:17]
	v_mul_f32_e32 v33, 0x3e38aa3b, v35
	v_cndmask_b32_e64 v125, v239, v33, s[16:17]
	s_waitcnt lgkmcnt(0)
	v_mfma_f32_32x32x16_bf16 v[16:31], v[112:115], v[108:111], v[16:31]
	ds_read_b128 v[108:111], v186 offset:96
	v_cndmask_b32_e64 v112, v239, v48, s[16:17]
	v_mul_f32_e32 v48, 0x3e38aa3b, v49
	v_mul_f32_e32 v49, 0x3e38aa3b, v50
	v_cndmask_b32_e64 v50, v239, v49, s[16:17]
	v_mul_f32_e32 v49, 0x3e38aa3b, v51
	v_cndmask_b32_e64 v51, v239, v49, s[16:17]
	s_waitcnt lgkmcnt(0)
	v_mfma_f32_32x32x16_bf16 v[16:31], v[108:111], v[104:107], v[16:31]
	v_cndmask_b32_e64 v104, v239, v66, s[86:87]
	v_mul_f32_e32 v66, 0x3e38aa3b, v67
	v_cndmask_b32_e64 v105, v239, v66, s[88:89]
	v_mul_f32_e32 v66, 0x3e38aa3b, v68
	v_cndmask_b32_e64 v106, v239, v66, s[90:91]
	v_mul_f32_e32 v66, 0x3e38aa3b, v69
	v_cndmask_b32_e64 v69, v239, v66, s[92:93]
	v_mul_f32_e32 v66, 0x3e38aa3b, v70
	v_cndmask_b32_e64 v107, v239, v66, s[94:95]
	v_mul_f32_e32 v66, 0x3e38aa3b, v71
	v_cndmask_b32_e64 v71, v239, v66, s[96:97]
	v_mul_f32_e32 v66, 0x3e38aa3b, v72
	v_cndmask_b32_e64 v72, v239, v66, s[28:29]
	v_mul_f32_e32 v66, 0x3e38aa3b, v73
	v_cndmask_b32_e64 v108, v239, v66, s[4:5]
	v_mul_f32_e32 v66, 0x3e38aa3b, v74
	v_max3_f32 v65, v65, v104, v105
	v_cndmask_b32_e64 v74, v239, v66, s[6:7]
	v_mul_f32_e32 v66, 0x3e38aa3b, v75
	v_max3_f32 v65, v65, v106, v69
	v_cndmask_b32_e64 v109, v239, v66, s[8:9]
	v_mul_f32_e32 v66, 0x3e38aa3b, v76
	v_mul_f32_e32 v49, 0x3e38aa3b, v52
	v_max3_f32 v65, v65, v107, v71
	v_cndmask_b32_e64 v110, v239, v66, s[10:11]
	v_mul_f32_e32 v66, 0x3e38aa3b, v77
	v_cndmask_b32_e64 v52, v239, v49, s[16:17]
	v_mul_f32_e32 v49, 0x3e38aa3b, v53
	v_max3_f32 v65, v65, v72, v108
	v_cndmask_b32_e64 v77, v239, v66, s[12:13]
	v_mul_f32_e32 v66, 0x3e38aa3b, v78
	v_cndmask_b32_e64 v53, v239, v49, s[16:17]
	v_mul_f32_e32 v49, 0x3e38aa3b, v54
	v_max3_f32 v65, v65, v74, v109
	v_cndmask_b32_e64 v111, v239, v66, s[14:15]
	v_mul_f32_e32 v66, 0x3e38aa3b, v79
	v_cndmask_b32_e64 v54, v239, v49, s[16:17]
	v_mul_f32_e32 v49, 0x3e38aa3b, v55
	v_max3_f32 v65, v65, v110, v77
	v_cndmask_b32_e64 v79, v239, v66, s[18:19]
	v_cndmask_b32_e64 v114, v239, v49, s[16:17]
	v_mul_f32_e32 v49, 0x3e38aa3b, v56
	v_max3_f32 v65, v65, v111, v79
	v_cndmask_b32_e64 v113, v239, v48, s[16:17]
	v_cndmask_b32_e64 v115, v239, v49, s[16:17]
	v_mul_f32_e32 v49, 0x3e38aa3b, v57
	v_max3_f32 v48, v65, v112, v113
	v_cndmask_b32_e64 v57, v239, v49, s[16:17]
	v_mul_f32_e32 v49, 0x3e38aa3b, v58
	v_max3_f32 v48, v48, v50, v51
	v_cndmask_b32_e64 v116, v239, v49, s[16:17]
	v_mul_f32_e32 v49, 0x3e38aa3b, v59
	v_max3_f32 v48, v48, v52, v53
	v_cndmask_b32_e64 v117, v239, v49, s[16:17]
	v_mul_f32_e32 v49, 0x3e38aa3b, v60
	v_mul_f32_e32 v33, 0x3e38aa3b, v36
	v_max3_f32 v48, v48, v54, v114
	v_cndmask_b32_e64 v118, v239, v49, s[16:17]
	v_mul_f32_e32 v49, 0x3e38aa3b, v61
	v_cndmask_b32_e64 v126, v239, v33, s[16:17]
	v_mul_f32_e32 v33, 0x3e38aa3b, v37
	v_max3_f32 v48, v48, v115, v57
	v_cndmask_b32_e64 v119, v239, v49, s[16:17]
	v_mul_f32_e32 v49, 0x3e38aa3b, v62
	v_cndmask_b32_e64 v127, v239, v33, s[16:17]
	v_mul_f32_e32 v33, 0x3e38aa3b, v38
	v_max3_f32 v48, v48, v116, v117
	v_cndmask_b32_e64 v120, v239, v49, s[16:17]
	v_mul_f32_e32 v49, 0x3e38aa3b, v63
	v_cndmask_b32_e64 v128, v239, v33, s[16:17]
	v_mul_f32_e32 v33, 0x3e38aa3b, v39
	v_max3_f32 v48, v48, v118, v119
	v_cndmask_b32_e64 v121, v239, v49, s[16:17]
	v_cndmask_b32_e64 v78, v239, v33, s[16:17]
	v_mul_f32_e32 v33, 0x3e38aa3b, v40
	v_max3_f32 v48, v48, v120, v121
	v_cndmask_b32_e64 v123, v239, v32, s[16:17]
	v_cndmask_b32_e64 v67, v239, v33, s[16:17]
	v_mul_f32_e32 v33, 0x3e38aa3b, v41
	v_max3_f32 v32, v48, v122, v123
	v_cndmask_b32_e64 v70, v239, v33, s[16:17]
	v_mul_f32_e32 v33, 0x3e38aa3b, v42
	v_max3_f32 v32, v32, v124, v125
	v_cndmask_b32_e64 v76, v239, v33, s[16:17]
	v_mul_f32_e32 v33, 0x3e38aa3b, v43
	v_max3_f32 v32, v32, v126, v127
	v_cndmask_b32_e64 v75, v239, v33, s[16:17]
	v_mul_f32_e32 v33, 0x3e38aa3b, v44
	v_max3_f32 v32, v32, v128, v78
	v_cndmask_b32_e64 v73, v239, v33, s[16:17]
	v_mul_f32_e32 v33, 0x3e38aa3b, v45
	v_max3_f32 v32, v32, v67, v70
	v_cndmask_b32_e64 v68, v239, v33, s[16:17]
	v_mul_f32_e32 v33, 0x3e38aa3b, v46
	v_max3_f32 v32, v32, v76, v75
	v_cndmask_b32_e64 v66, v239, v33, s[16:17]
	v_mul_f32_e32 v33, 0x3e38aa3b, v47
	v_max3_f32 v32, v32, v73, v68
	v_cndmask_b32_e64 v65, v239, v33, s[16:17]
	v_max3_f32 v32, v32, v66, v65
	v_mul_f32_e32 v33, 0x3e38aa3b, v0
	v_mul_f32_e32 v34, 0x3e38aa3b, v1
	v_mul_f32_e32 v16, 0x3e38aa3b, v16
	v_max3_f32 v32, v32, v33, v34
	v_mul_f32_e32 v33, 0x3e38aa3b, v2
	v_mul_f32_e32 v34, 0x3e38aa3b, v3
	v_cndmask_b32_e64 v46, v16, v239, s[52:53]
	v_mul_f32_e32 v16, 0x3e38aa3b, v17
	v_mul_f32_e32 v17, 0x3e38aa3b, v18
	v_max3_f32 v32, v32, v33, v34
	v_mul_f32_e32 v33, 0x3e38aa3b, v4
	v_mul_f32_e32 v34, 0x3e38aa3b, v5
	v_cndmask_b32_e64 v48, v17, v239, s[48:49]
	v_mul_f32_e32 v17, 0x3e38aa3b, v19
	v_max3_f32 v32, v32, v33, v34
	v_mul_f32_e32 v33, 0x3e38aa3b, v6
	v_mul_f32_e32 v34, 0x3e38aa3b, v7
	v_cndmask_b32_e64 v56, v17, v239, s[56:57]
	v_mul_f32_e32 v17, 0x3e38aa3b, v20
	v_max3_f32 v32, v32, v33, v34
	v_mul_f32_e32 v33, 0x3e38aa3b, v8
	v_mul_f32_e32 v34, 0x3e38aa3b, v9
	v_cndmask_b32_e64 v58, v17, v239, s[38:39]
	v_mul_f32_e32 v17, 0x3e38aa3b, v21
	v_max3_f32 v32, v32, v33, v34
	v_mul_f32_e32 v33, 0x3e38aa3b, v10
	v_mul_f32_e32 v34, 0x3e38aa3b, v11
	v_cndmask_b32_e64 v59, v17, v239, s[2:3]
	v_mul_f32_e32 v17, 0x3e38aa3b, v22
	v_max3_f32 v32, v32, v33, v34
	v_mul_f32_e32 v33, 0x3e38aa3b, v12
	v_mul_f32_e32 v34, 0x3e38aa3b, v13
	v_cndmask_b32_e64 v61, v17, v239, s[40:41]
	v_mul_f32_e32 v17, 0x3e38aa3b, v23
	v_max3_f32 v32, v32, v33, v34
	v_mul_f32_e32 v33, 0x3e38aa3b, v14
	v_mul_f32_e32 v34, 0x3e38aa3b, v15
	v_cndmask_b32_e64 v63, v17, v239, s[42:43]
	v_mul_f32_e32 v17, 0x3e38aa3b, v24
	v_max3_f32 v32, v32, v33, v34
	v_cndmask_b32_e64 v47, v239, v16, s[0:1]
	v_cndmask_b32_e64 v24, v17, v239, s[44:45]
	v_mul_f32_e32 v17, 0x3e38aa3b, v25
	v_max3_f32 v16, v32, v46, v47
	v_cndmask_b32_e64 v25, v17, v239, s[68:69]
	v_mul_f32_e32 v17, 0x3e38aa3b, v26
	v_max3_f32 v16, v16, v48, v56
	v_cndmask_b32_e64 v26, v17, v239, s[70:71]
	v_mul_f32_e32 v17, 0x3e38aa3b, v27
	v_max3_f32 v16, v16, v58, v59
	v_cndmask_b32_e64 v27, v17, v239, s[72:73]
	v_mul_f32_e32 v17, 0x3e38aa3b, v28
	v_max3_f32 v16, v16, v61, v63
	v_cndmask_b32_e64 v28, v17, v239, s[74:75]
	v_mul_f32_e32 v17, 0x3e38aa3b, v29
	v_max3_f32 v16, v16, v24, v25
	v_cndmask_b32_e64 v29, v17, v239, s[76:77]
	v_mul_f32_e32 v17, 0x3e38aa3b, v30
	v_max3_f32 v16, v16, v26, v27
	v_cndmask_b32_e64 v30, v17, v239, s[78:79]
	v_mul_f32_e32 v17, 0x3e38aa3b, v31
	v_max3_f32 v16, v16, v28, v29
	v_cndmask_b32_e64 v31, v17, v239, s[36:37]
	v_max3_f32 v16, v16, v30, v31
	ds_bpermute_b32 v17, v189, v16
	s_mov_b32 s0, 0x3e38aa3b
	s_waitcnt lgkmcnt(0)
	v_max_f32_e32 v17, v17, v17
	v_max_f32_e32 v130, v16, v17
	v_sub_f32_e32 v16, v64, v130
	v_exp_f32_e32 v16, v16
	v_sub_f32_e32 v17, v80, v130
	v_exp_f32_e32 v17, v17
	v_sub_f32_e32 v36, v109, v130
	v_add_f32_e32 v18, 0, v16
	v_exp_f32_e32 v36, v36
	v_add_f32_e32 v19, v18, v17
	v_sub_f32_e32 v18, v104, v130
	v_exp_f32_e32 v18, v18
	v_sub_f32_e32 v37, v110, v130
	v_exp_f32_e32 v38, v37
	v_sub_f32_e32 v37, v77, v130
	v_add_f32_e32 v20, v19, v18
	v_sub_f32_e32 v19, v105, v130
	v_exp_f32_e32 v19, v19
	v_exp_f32_e32 v39, v37
	v_sub_f32_e32 v37, v111, v130
	v_exp_f32_e32 v44, v37
	v_add_f32_e32 v21, v20, v19
	v_sub_f32_e32 v20, v106, v130
	v_exp_f32_e32 v20, v20
	v_sub_f32_e32 v37, v79, v130
	v_exp_f32_e32 v49, v37
	v_sub_f32_e32 v42, v51, v130
	v_add_f32_e32 v22, v21, v20
	v_sub_f32_e32 v21, v69, v130
	v_exp_f32_e32 v21, v21
	v_exp_f32_e32 v42, v42
	v_sub_f32_e32 v43, v52, v130
	v_exp_f32_e32 v45, v43
	v_add_f32_e32 v23, v22, v21
	v_sub_f32_e32 v22, v107, v130
	v_exp_f32_e32 v22, v22
	v_sub_f32_e32 v43, v53, v130
	v_sub_f32_e32 v53, v117, v130
	v_exp_f32_e32 v53, v53
	v_add_f32_e32 v32, v23, v22
	v_sub_f32_e32 v23, v71, v130
	v_exp_f32_e32 v23, v23
	v_sub_f32_e32 v80, v128, v130
	v_exp_f32_e32 v109, v80
	v_sub_f32_e32 v78, v78, v130
	v_add_f32_e32 v33, v32, v23
	v_sub_f32_e32 v32, v72, v130
	v_exp_f32_e32 v32, v32
	v_sub_f32_e32 v67, v67, v130
	v_exp_f32_e32 v67, v67
	v_sub_f32_e32 v70, v70, v130
	v_add_f32_e32 v34, v33, v32
	v_sub_f32_e32 v33, v108, v130
	v_exp_f32_e32 v33, v33
	v_exp_f32_e32 v70, v70
	v_sub_f32_e32 v76, v76, v130
	v_sub_f32_e32 v75, v75, v130
	v_add_f32_e32 v35, v34, v33
	v_sub_f32_e32 v34, v74, v130
	v_exp_f32_e32 v34, v34
	v_exp_f32_e32 v107, v75
	v_sub_f32_e32 v73, v73, v130
	v_exp_f32_e32 v111, v73
	v_add_f32_e32 v35, v35, v34
	v_add_f32_e32 v35, v35, v36
	v_add_f32_e32 v35, v35, v38
	v_add_f32_e32 v35, v35, v39
	v_add_f32_e32 v35, v35, v44
	v_add_f32_e32 v37, v35, v49
	v_sub_f32_e32 v35, v112, v130
	v_exp_f32_e32 v35, v35
	v_exp_f32_e32 v112, v78
	v_sub_f32_e32 v68, v68, v130
	v_sub_f32_e32 v66, v66, v130
	v_add_f32_e32 v40, v37, v35
	v_sub_f32_e32 v37, v113, v130
	v_exp_f32_e32 v37, v37
	v_sub_f32_e32 v65, v65, v130
	v_fma_f32 v0, v0, s0, -v130
	v_exp_f32_e32 v104, v0
	v_add_f32_e32 v41, v40, v37
	v_sub_f32_e32 v40, v50, v130
	v_exp_f32_e32 v40, v40
	v_exp_f32_e32 v50, v43
	v_sub_f32_e32 v43, v54, v130
	v_exp_f32_e32 v55, v43
	v_add_f32_e32 v41, v41, v40
	v_sub_f32_e32 v43, v114, v130
	v_add_f32_e32 v41, v41, v42
	v_exp_f32_e32 v60, v43
	v_add_f32_e32 v41, v41, v45
	v_add_f32_e32 v41, v41, v50
	v_add_f32_e32 v41, v41, v55
	v_add_f32_e32 v43, v41, v60
	v_sub_f32_e32 v41, v115, v130
	v_exp_f32_e32 v41, v41
	v_sub_f32_e32 v54, v118, v130
	v_exp_f32_e32 v114, v68
	v_fma_f32 v1, v1, s0, -v130
	v_add_f32_e32 v51, v43, v41
	v_sub_f32_e32 v43, v57, v130
	v_exp_f32_e32 v43, v43
	v_exp_f32_e32 v57, v54
	v_sub_f32_e32 v54, v119, v130
	v_exp_f32_e32 v62, v54
	v_add_f32_e32 v52, v51, v43
	v_sub_f32_e32 v51, v116, v130
	v_exp_f32_e32 v51, v51
	v_sub_f32_e32 v54, v120, v130
	v_exp_f32_e32 v71, v54
	v_sub_f32_e32 v54, v121, v130
	v_add_f32_e32 v52, v52, v51
	v_add_f32_e32 v52, v52, v53
	v_exp_f32_e32 v74, v54
	v_add_f32_e32 v52, v52, v57
	v_add_f32_e32 v52, v52, v62
	v_add_f32_e32 v52, v52, v71
	v_add_f32_e32 v54, v52, v74
	v_sub_f32_e32 v52, v122, v130
	v_exp_f32_e32 v52, v52
	v_exp_f32_e32 v110, v1
	v_fma_f32 v1, v2, s0, -v130
	v_exp_f32_e32 v117, v1
	v_add_f32_e32 v64, v54, v52
	v_sub_f32_e32 v54, v123, v130
	v_exp_f32_e32 v54, v54
	v_exp_f32_e32 v123, v66
	v_fma_f32 v1, v3, s0, -v130
	v_exp_f32_e32 v121, v1
	v_add_f32_e32 v69, v64, v54
	v_sub_f32_e32 v64, v124, v130
	v_exp_f32_e32 v64, v64
	v_fma_f32 v1, v4, s0, -v130
	v_add_f32_e32 v72, v69, v64
	v_sub_f32_e32 v69, v125, v130
	v_exp_f32_e32 v69, v69
	v_exp_f32_e32 v125, v1
	v_fma_f32 v1, v5, s0, -v130
	v_add_f32_e32 v77, v72, v69
	v_sub_f32_e32 v72, v126, v130
	v_exp_f32_e32 v72, v72
	v_exp_f32_e32 v126, v65
	v_add_f32_e32 v79, v77, v72
	v_sub_f32_e32 v77, v127, v130
	v_exp_f32_e32 v77, v77
	v_exp_f32_e32 v127, v1
	v_fma_f32 v1, v6, s0, -v130
	v_exp_f32_e32 v128, v1
	v_add_f32_e32 v79, v79, v77
	v_add_f32_e32 v79, v79, v109
	v_add_f32_e32 v78, v79, v112
	v_exp_f32_e32 v79, v76
	v_add_f32_e32 v78, v78, v67
	v_add_f32_e32 v78, v78, v70
	v_fma_f32 v1, v7, s0, -v130
	v_add_f32_e32 v76, v78, v79
	v_add_f32_e32 v75, v76, v107
	v_add_f32_e32 v73, v75, v111
	v_add_f32_e32 v68, v73, v114
	v_add_f32_e32 v66, v68, v123
	v_add_f32_e32 v65, v66, v126
	v_add_f32_e32 v0, v65, v104
	v_add_f32_e32 v0, v0, v110
	v_add_f32_e32 v0, v0, v117
	v_add_f32_e32 v0, v0, v121
	v_exp_f32_e32 v129, v1
	v_fma_f32 v1, v8, s0, -v130
	v_add_f32_e32 v0, v0, v125
	v_exp_f32_e32 v113, v1
	v_fma_f32 v1, v9, s0, -v130
	v_add_f32_e32 v0, v0, v127
	v_exp_f32_e32 v115, v1
	v_fma_f32 v1, v10, s0, -v130
	v_add_f32_e32 v0, v0, v128
	v_exp_f32_e32 v116, v1
	v_fma_f32 v1, v11, s0, -v130
	v_add_f32_e32 v0, v0, v129
	v_exp_f32_e32 v118, v1
	v_fma_f32 v1, v12, s0, -v130
	v_add_f32_e32 v0, v0, v113
	v_exp_f32_e32 v119, v1
	v_fma_f32 v1, v13, s0, -v130
	v_add_f32_e32 v0, v0, v115
	v_exp_f32_e32 v120, v1
	v_fma_f32 v1, v14, s0, -v130
	v_add_f32_e32 v0, v0, v116
	v_exp_f32_e32 v122, v1
	v_fma_f32 v1, v15, s0, -v130
	v_add_f32_e32 v0, v0, v118
	v_exp_f32_e32 v124, v1
	v_sub_f32_e32 v1, v46, v130
	v_add_f32_e32 v0, v0, v119
	v_exp_f32_e32 v73, v1
	v_sub_f32_e32 v1, v47, v130
	v_add_f32_e32 v0, v0, v120
	v_exp_f32_e32 v75, v1
	v_sub_f32_e32 v1, v48, v130
	v_add_f32_e32 v0, v0, v122
	v_exp_f32_e32 v76, v1
	v_sub_f32_e32 v1, v56, v130
	v_add_f32_e32 v0, v0, v124
	v_exp_f32_e32 v78, v1
	v_sub_f32_e32 v1, v58, v130
	v_add_f32_e32 v0, v0, v73
	v_exp_f32_e32 v80, v1
	v_sub_f32_e32 v1, v59, v130
	v_add_f32_e32 v0, v0, v75
	v_exp_f32_e32 v105, v1
	v_sub_f32_e32 v1, v61, v130
	v_add_f32_e32 v0, v0, v76
	v_exp_f32_e32 v106, v1
	v_sub_f32_e32 v1, v63, v130
	v_add_f32_e32 v0, v0, v78
	v_exp_f32_e32 v108, v1
	v_sub_f32_e32 v1, v24, v130
	v_add_f32_e32 v0, v0, v80
	v_exp_f32_e32 v56, v1
	v_sub_f32_e32 v1, v25, v130
	v_add_f32_e32 v0, v0, v105
	v_exp_f32_e32 v58, v1
	v_sub_f32_e32 v1, v26, v130
	v_add_f32_e32 v0, v0, v106
	v_exp_f32_e32 v59, v1
	v_sub_f32_e32 v1, v27, v130
	v_add_f32_e32 v0, v0, v108
	v_exp_f32_e32 v61, v1
	v_sub_f32_e32 v1, v28, v130
	v_add_f32_e32 v0, v0, v56
	v_exp_f32_e32 v63, v1
	v_sub_f32_e32 v1, v29, v130
	v_add_f32_e32 v0, v0, v58
	v_exp_f32_e32 v65, v1
	v_sub_f32_e32 v1, v30, v130
	v_add_f32_e32 v0, v0, v59
	v_exp_f32_e32 v66, v1
	v_sub_f32_e32 v1, v31, v130
	v_add_f32_e32 v0, v0, v61
	v_exp_f32_e32 v68, v1
	v_add_f32_e32 v0, v0, v63
	v_add_f32_e32 v0, v0, v65
	v_add_f32_e32 v0, v0, v66
	s_mov_b32 s0, 0x3fb8aa3b
	v_add_f32_e32 v46, v0, v68
	v_fma_f32 v0, v188, s0, -v130
	v_exp_f32_e32 v48, v0
	v_cvt_pk_bf16_f32 v0, v16, v17
	v_cvt_pk_bf16_f32 v1, v18, v19
	v_cvt_pk_bf16_f32 v2, v20, v21
	v_cvt_pk_bf16_f32 v3, v22, v23
	ds_read_b128 v[4:7], v182 offset:36864
	ds_read_b128 v[8:11], v182 offset:53760
	s_waitcnt lgkmcnt(1)
	v_mfma_f32_32x32x16_bf16 v[16:31], v[4:7], v[0:3], 0
	ds_bpermute_b32 v47, v189, v46
	v_cvt_pk_bf16_f32 v188, v32, v33
	v_cvt_pk_bf16_f32 v189, v34, v36
	v_cvt_pk_bf16_f32 v190, v38, v39
	v_cvt_pk_bf16_f32 v191, v44, v49
	ds_read_b128 v[192:195], v182 offset:36896
	ds_read_b128 v[196:199], v182 offset:53792
	v_cvt_pk_bf16_f32 v32, v35, v37
	s_waitcnt lgkmcnt(3)
	v_mfma_f32_32x32x16_bf16 v[0:15], v[8:11], v[0:3], 0
	v_cvt_pk_bf16_f32 v33, v40, v42
	v_cvt_pk_bf16_f32 v34, v45, v50
	v_cvt_pk_bf16_f32 v35, v55, v60
	s_waitcnt lgkmcnt(1)
	v_mfma_f32_32x32x16_bf16 v[16:31], v[192:195], v[188:191], v[16:31]
	s_waitcnt lgkmcnt(0)
	v_mfma_f32_32x32x16_bf16 v[0:15], v[196:199], v[188:191], v[0:15]
	ds_read_b128 v[84:87], v183 offset:36864
	ds_read_b128 v[88:91], v183 offset:53760
	ds_read_b128 v[92:95], v183 offset:36896
	ds_read_b128 v[96:99], v183 offset:53792
	s_waitcnt lgkmcnt(3)
	v_mfma_f32_32x32x16_bf16 v[16:31], v[84:87], v[32:35], v[16:31]
	s_waitcnt lgkmcnt(2)
	v_mfma_f32_32x32x16_bf16 v[0:15], v[88:91], v[32:35], v[0:15]
	v_cvt_pk_bf16_f32 v32, v41, v43
	v_cvt_pk_bf16_f32 v33, v51, v53
	v_cvt_pk_bf16_f32 v34, v57, v62
	v_cvt_pk_bf16_f32 v35, v71, v74
	ds_read_b128 v[84:87], v184 offset:36864
	ds_read_b128 v[88:91], v184 offset:53760
	s_waitcnt lgkmcnt(3)
	v_mfma_f32_32x32x16_bf16 v[16:31], v[92:95], v[32:35], v[16:31]
	s_waitcnt lgkmcnt(2)
	v_mfma_f32_32x32x16_bf16 v[0:15], v[96:99], v[32:35], v[0:15]
	v_cvt_pk_bf16_f32 v32, v52, v54
	v_cvt_pk_bf16_f32 v33, v64, v69
	v_cvt_pk_bf16_f32 v34, v72, v77
	v_cvt_pk_bf16_f32 v35, v109, v112
	ds_read_b128 v[92:95], v184 offset:36896
	ds_read_b128 v[96:99], v184 offset:53792
	s_waitcnt lgkmcnt(3)
	v_mfma_f32_32x32x16_bf16 v[16:31], v[84:87], v[32:35], v[16:31]
	s_waitcnt lgkmcnt(2)
	v_mfma_f32_32x32x16_bf16 v[0:15], v[88:91], v[32:35], v[0:15]
	v_cvt_pk_bf16_f32 v32, v67, v70
	v_cvt_pk_bf16_f32 v33, v79, v107
	v_cvt_pk_bf16_f32 v34, v111, v114
	v_cvt_pk_bf16_f32 v35, v123, v126
	ds_read_b128 v[84:87], v185 offset:36864
	ds_read_b128 v[88:91], v185 offset:53760
	s_waitcnt lgkmcnt(3)
	v_mfma_f32_32x32x16_bf16 v[16:31], v[92:95], v[32:35], v[16:31]
	s_waitcnt lgkmcnt(2)
	v_mfma_f32_32x32x16_bf16 v[0:15], v[96:99], v[32:35], v[0:15]
	v_cvt_pk_bf16_f32 v32, v104, v110
	v_cvt_pk_bf16_f32 v33, v117, v121
	v_cvt_pk_bf16_f32 v34, v125, v127
	v_cvt_pk_bf16_f32 v35, v128, v129
	ds_read_b128 v[92:95], v185 offset:36896
	ds_read_b128 v[96:99], v185 offset:53792
	s_waitcnt lgkmcnt(3)
	v_mfma_f32_32x32x16_bf16 v[16:31], v[84:87], v[32:35], v[16:31]
	s_waitcnt lgkmcnt(2)
	v_mfma_f32_32x32x16_bf16 v[0:15], v[88:91], v[32:35], v[0:15]
	v_cvt_pk_bf16_f32 v32, v113, v115
	v_cvt_pk_bf16_f32 v33, v116, v118
	v_cvt_pk_bf16_f32 v34, v119, v120
	v_cvt_pk_bf16_f32 v35, v122, v124
	ds_read_b128 v[84:87], v187 offset:36864
	ds_read_b128 v[88:91], v187 offset:53760
	s_waitcnt lgkmcnt(3)
	v_mfma_f32_32x32x16_bf16 v[16:31], v[92:95], v[32:35], v[16:31]
	s_waitcnt lgkmcnt(2)
	v_mfma_f32_32x32x16_bf16 v[0:15], v[96:99], v[32:35], v[0:15]
	v_cvt_pk_bf16_f32 v32, v73, v75
	v_cvt_pk_bf16_f32 v33, v76, v78
	v_cvt_pk_bf16_f32 v34, v80, v105
	v_cvt_pk_bf16_f32 v35, v106, v108
	ds_read_b128 v[92:95], v187 offset:36896
	ds_read_b128 v[96:99], v187 offset:53792
	s_waitcnt lgkmcnt(3)
	v_mfma_f32_32x32x16_bf16 v[16:31], v[84:87], v[32:35], v[16:31]
	s_waitcnt lgkmcnt(2)
	v_mfma_f32_32x32x16_bf16 v[0:15], v[88:91], v[32:35], v[0:15]
	v_cvt_pk_bf16_f32 v32, v56, v58
	v_cvt_pk_bf16_f32 v33, v59, v61
	v_cvt_pk_bf16_f32 v34, v63, v65
	v_cvt_pk_bf16_f32 v35, v66, v68
	s_waitcnt lgkmcnt(1)
	v_mfma_f32_32x32x16_bf16 v[16:31], v[92:95], v[32:35], v[16:31]
	s_waitcnt lgkmcnt(0)
	v_mfma_f32_32x32x16_bf16 v[0:15], v[96:99], v[32:35], v[0:15]
	v_add_f32_e32 v32, v46, v47
	v_add_f32_e32 v32, v48, v32
	v_div_scale_f32 v33, s[0:1], v32, v32, 1.0
	v_rcp_f32_e32 v34, v33
	s_mov_b64 s[0:1], 0
	v_fma_f32 v35, -v33, v34, 1.0
	v_fmac_f32_e32 v34, v35, v34
	v_div_scale_f32 v35, vcc, 1.0, v32, 1.0
	v_mul_f32_e32 v36, v35, v34
	v_fma_f32 v37, -v33, v36, v35
	v_fmac_f32_e32 v36, v37, v34
	v_fma_f32 v33, -v33, v36, v35
	v_div_fmas_f32 v33, v33, v34, v36
	v_div_fixup_f32 v34, v33, v32, 1.0
	v_lshrrev_b64 v[32:33], 2, v[160:161]
	v_and_b32_e32 v33, 0x3ffff, v33
	v_and_b32_e32 v32, 0xffffffe0, v32
	v_lshlrev_b32_e32 v35, 6, v160
	v_lshlrev_b32_e32 v37, 2, v160
	v_lshl_add_u64 v[32:33], v[32:33], 0, s[34:35]
	v_and_b32_e32 v35, 0x3c0, v35
	v_lshlrev_b32_e32 v36, 7, v160
	v_and_b32_e32 v37, 32, v37
	v_and_b32_e32 v36, 0x3800, v36
	v_lshlrev_b64 v[32:33], 14, v[32:33]
	v_mul_f32_e32 v16, v34, v16
	v_mul_f32_e32 v17, v34, v17
	v_or3_b32 v39, v137, v35, v37
	v_lshl_add_u64 v[32:33], s[80:81], 0, v[32:33]
	v_cvt_pk_bf16_f32 v16, v16, v17
	v_mul_f32_e32 v17, v34, v18
	v_mul_f32_e32 v18, v34, v19
	v_or_b32_e32 v80, v39, v36
	v_or_b32_e32 v38, 0x400, v36
	v_cvt_pk_bf16_f32 v17, v17, v18
	v_lshl_add_u64 v[18:19], v[32:33], 0, v[80:81]
	v_mul_f32_e32 v0, v34, v0
	v_mul_f32_e32 v1, v34, v1
	global_store_dwordx2 v[18:19], v[16:17], off
	v_cvt_pk_bf16_f32 v0, v0, v1
	v_mul_f32_e32 v1, v34, v2
	v_mul_f32_e32 v2, v34, v3
	v_or_b32_e32 v80, v39, v38
	v_cvt_pk_bf16_f32 v1, v1, v2
	v_lshl_add_u64 v[2:3], v[32:33], 0, v[80:81]
	global_store_dwordx2 v[2:3], v[0:1], off
	v_mul_f32_e32 v0, v34, v20
	v_mul_f32_e32 v1, v34, v21
	v_or3_b32 v16, v165, v35, v37
	v_cvt_pk_bf16_f32 v0, v0, v1
	v_mul_f32_e32 v1, v34, v22
	v_mul_f32_e32 v2, v34, v23
	v_or_b32_e32 v80, v16, v36
	v_cvt_pk_bf16_f32 v1, v1, v2
	v_lshl_add_u64 v[2:3], v[32:33], 0, v[80:81]
	global_store_dwordx2 v[2:3], v[0:1], off
	v_mul_f32_e32 v0, v34, v4
	v_mul_f32_e32 v1, v34, v5
	v_cvt_pk_bf16_f32 v0, v0, v1
	v_mul_f32_e32 v1, v34, v6
	v_mul_f32_e32 v2, v34, v7
	v_or_b32_e32 v80, v16, v38
	v_cvt_pk_bf16_f32 v1, v1, v2
	v_lshl_add_u64 v[2:3], v[32:33], 0, v[80:81]
	global_store_dwordx2 v[2:3], v[0:1], off
	v_mul_f32_e32 v0, v34, v24
	v_mul_f32_e32 v1, v34, v25
	v_bitop3_b32 v4, v166, v37, v35 bitop3:0x36
	v_cvt_pk_bf16_f32 v0, v0, v1
	v_mul_f32_e32 v1, v34, v26
	v_mul_f32_e32 v2, v34, v27
	v_or_b32_e32 v80, v4, v36
	v_cvt_pk_bf16_f32 v1, v1, v2
	v_lshl_add_u64 v[2:3], v[32:33], 0, v[80:81]
	global_store_dwordx2 v[2:3], v[0:1], off
	v_mul_f32_e32 v0, v34, v8
	v_mul_f32_e32 v1, v34, v9
	v_cvt_pk_bf16_f32 v0, v0, v1
	v_mul_f32_e32 v1, v34, v10
	v_mul_f32_e32 v2, v34, v11
	v_or_b32_e32 v80, v4, v38
	v_cvt_pk_bf16_f32 v1, v1, v2
	v_lshl_add_u64 v[2:3], v[32:33], 0, v[80:81]
	global_store_dwordx2 v[2:3], v[0:1], off
	v_mul_f32_e32 v0, v34, v28
	v_mul_f32_e32 v1, v34, v29
	v_bitop3_b32 v4, v167, v37, v35 bitop3:0x36
	v_cvt_pk_bf16_f32 v0, v0, v1
	v_mul_f32_e32 v1, v34, v30
	v_mul_f32_e32 v2, v34, v31
	v_or_b32_e32 v80, v4, v36
	v_cvt_pk_bf16_f32 v1, v1, v2
	v_lshl_add_u64 v[2:3], v[32:33], 0, v[80:81]
	global_store_dwordx2 v[2:3], v[0:1], off
	v_mul_f32_e32 v0, v34, v12
	v_mul_f32_e32 v1, v34, v13
	v_cvt_pk_bf16_f32 v0, v0, v1
	v_mul_f32_e32 v1, v34, v14
	v_mul_f32_e32 v2, v34, v15
	v_or_b32_e32 v80, v4, v38
	v_cvt_pk_bf16_f32 v1, v1, v2
	v_lshl_add_u64 v[2:3], v[32:33], 0, v[80:81]
	global_store_dwordx2 v[2:3], v[0:1], off
